# v16 + NA tile loop: Q fragment loads waited once before the loop; the per-tile QK waits no longer drain the K/V prefetch loads (counted vmcnt)
# baseline (speedup 1.0000x reference)
.LBB0_217:
	s_or_b64 exec, exec, s[64:65]
	v_lshl_add_u64 v[4:5], v[118:119], 1, v[164:165]
	v_lshl_add_u64 v[6:7], v[124:125], 1, v[110:111]
	global_load_dwordx4 v[96:99], v[4:5], off
	global_load_dwordx4 v[100:103], v[6:7], off
	v_lshlrev_b64 v[162:163], 10, v[160:161]
	v_mov_b32_e32 v109, v1
	v_lshl_add_u64 v[2:3], s[2:3], 0, v[162:163]
	v_lshl_add_u64 v[164:165], s[48:49], 0, v[108:109]
	v_mad_i64_i32 v[166:167], s[2:3], s42, v128, 0
	v_lshl_add_u64 v[4:5], v[166:167], 1, v[164:165]
	v_mad_i64_i32 v[168:169], s[2:3], s42, v130, 0
	v_lshl_add_u64 v[2:3], v[2:3], 0, v[0:1]
	v_lshl_add_u64 v[6:7], v[168:169], 1, v[164:165]
	global_load_dwordx4 v[104:107], v[4:5], off
	global_load_dwordx4 v[108:111], v[6:7], off
	global_load_dwordx4 v[80:83], v[2:3], off
	global_load_dwordx4 v[84:87], v[2:3], off offset:32
	global_load_dwordx4 v[88:91], v[2:3], off offset:64
	global_load_dwordx4 v[92:95], v[2:3], off offset:96
	s_lshl_b32 s2, s74, 1
	v_sub_u32_e64 v3, s2, 4 clamp
	v_sub_u32_e64 v4, s2, 3 clamp
	v_readfirstlane_b32 s2, v3
	v_readfirstlane_b32 s3, v4
	s_min_u32 s2, s2, 56
	s_min_u32 s3, s3, 56
	s_sub_i32 s69, s3, s2
	s_add_i32 s68, s69, 8
	s_cmp_gt_i32 s68, -8
	v_add3_u32 v0, v131, v202, s33
	v_add3_u32 v2, v131, v203, s33
	s_waitcnt vmcnt(7)
	ds_write_b128 v145, v[96:99]
	s_waitcnt vmcnt(6)
	ds_write_b128 v149, v[100:103]
	s_waitcnt vmcnt(5)
	ds_write2_b64 v0, v[104:105], v[106:107] offset1:1
	s_waitcnt vmcnt(4)
	ds_write2_b64 v2, v[108:109], v[110:111] offset1:1
	s_waitcnt lgkmcnt(0)
	s_barrier
	s_cbranch_scc0 .LBB0_182
	v_add_u32_e32 v0, s75, v233
	v_max_i32_e32 v2, 4, v0
	v_add_u32_e32 v2, -4, v2
	v_min_u32_e32 v145, 56, v2
	v_sub_u32_e64 v2, s75, 4 clamp
	s_movk_i32 s3, 0x7c
	v_readfirstlane_b32 s2, v2
	s_min_u32 s66, s2, 56
	s_mul_i32 s2, s66, 0x7c
	v_mul_lo_u32 v0, v0, s3
	v_sub_u32_e32 v0, s2, v0
	v_mov_b32_e32 v14, v1
	v_mov_b32_e32 v15, v1
	v_add_u32_e32 v153, v238, v0
	v_mov_b32_e32 v0, v1
	v_mov_b32_e32 v2, v1
	v_mov_b32_e32 v3, v1
	v_mov_b32_e32 v4, v1
	v_mov_b32_e32 v5, v1
	v_mov_b32_e32 v6, v1
	v_mov_b32_e32 v7, v1
	v_mov_b32_e32 v8, v1
	v_mov_b32_e32 v9, v1
	v_mov_b32_e32 v10, v1
	v_mov_b32_e32 v11, v1
	v_mov_b32_e32 v12, v1
	v_mov_b32_e32 v13, v1
	v_mov_b64_e32 v[30:31], v[14:15]
	v_mov_b64_e32 v[46:47], v[14:15]
	s_add_i32 s67, s66, -8
	v_add_u32_e32 v149, 8, v145
	s_add_i32 s68, s68, 7
	v_lshl_add_u64 v[170:171], v[118:119], 1, s[46:47]
	v_lshl_add_u64 v[172:173], v[124:125], 1, s[46:47]
	s_add_i32 s69, s69, 16
	s_mov_b32 s70, 0
	v_mov_b32_e32 v151, 0
	v_mov_b32_e32 v174, 0xff800000
	v_mov_b64_e32 v[28:29], v[12:13]
	v_mov_b64_e32 v[26:27], v[10:11]
	v_mov_b64_e32 v[24:25], v[8:9]
	v_mov_b64_e32 v[22:23], v[6:7]
	v_mov_b64_e32 v[20:21], v[4:5]
	v_mov_b64_e32 v[18:19], v[2:3]
	v_mov_b64_e32 v[16:17], v[0:1]
	v_mov_b64_e32 v[44:45], v[12:13]
	v_mov_b64_e32 v[42:43], v[10:11]
	v_mov_b64_e32 v[40:41], v[8:9]
	v_mov_b64_e32 v[38:39], v[6:7]
	v_mov_b64_e32 v[36:37], v[4:5]
	v_mov_b64_e32 v[34:35], v[2:3]
	v_mov_b64_e32 v[32:33], v[0:1]
	s_waitcnt vmcnt(0)
	s_branch .LBB0_220

.LBB0_224:
	s_and_saveexec_b64 s[46:47], s[42:43]
	s_cbranch_execz .LBB0_294
	s_bitcmp1_b32 s70, 0
	s_cselect_b32 s42, 0x4600, 0
	v_or_b32_e32 v0, s42, v204
	v_add_u32_e32 v0, v0, v205
	ds_read_b128 v[2:5], v0
	ds_read_b128 v[6:9], v0 offset:4608
	s_setprio 1
	ds_read_b128 v[10:13], v0 offset:32
	ds_read_b128 v[176:179], v0 offset:4640
	s_waitcnt lgkmcnt(3)
	v_mfma_f32_32x32x16_bf16 v[64:79], v[2:5], v[80:83], 0
	s_waitcnt lgkmcnt(2)
	v_mfma_f32_32x32x16_bf16 v[48:63], v[6:9], v[80:83], 0
	ds_read_b128 v[2:5], v0 offset:64
	ds_read_b128 v[6:9], v0 offset:4672
	s_waitcnt lgkmcnt(3)
	v_mfma_f32_32x32x16_bf16 v[64:79], v[10:13], v[84:87], v[64:79]
	s_waitcnt lgkmcnt(2)
	v_mfma_f32_32x32x16_bf16 v[48:63], v[176:179], v[84:87], v[48:63]
	ds_read_b128 v[10:13], v0 offset:96
	ds_read_b128 v[176:179], v0 offset:4704
	s_waitcnt lgkmcnt(3)
	v_mfma_f32_32x32x16_bf16 v[64:79], v[2:5], v[88:91], v[64:79]
	s_waitcnt lgkmcnt(2)
	v_mfma_f32_32x32x16_bf16 v[48:63], v[6:9], v[88:91], v[48:63]
	s_waitcnt lgkmcnt(1)
	v_mfma_f32_32x32x16_bf16 v[64:79], v[10:13], v[92:95], v[64:79]
	s_waitcnt lgkmcnt(0)
	v_mfma_f32_32x32x16_bf16 v[48:63], v[176:179], v[92:95], v[48:63]
	v_or_b32_e32 v0, s42, v112
	v_add_u32_e32 v0, v0, v232
	v_add_u32_e32 v155, 0x2000, v0
	v_add_u32_e32 v0, 0x3000, v0
	ds_read2_b64 v[2:5], v155 offset0:128 offset1:130
	ds_read2_b64 v[6:9], v0 offset0:160 offset1:162
	s_mov_b64 s[42:43], -1
	s_and_b64 vcc, exec, s[64:65]
	s_nop 2
	s_cbranch_vccz .LBB0_296
	s_add_i32 s42, s67, s70
	v_cmp_ge_i32_e32 vcc, s42, v145
	v_cmp_lt_i32_e64 s[42:43], s42, v149
	v_mov_b32_e32 v218, 0xff800000
	ds_read2_b32 v[10:11], v153 offset0:0 offset1:1
	ds_read2_b32 v[12:13], v153 offset0:2 offset1:3
	ds_read2_b32 v[14:15], v153 offset0:8 offset1:9
	ds_read2_b32 v[176:177], v153 offset0:10 offset1:11
	ds_read2_b32 v[178:179], v153 offset0:16 offset1:17
	ds_read2_b32 v[180:181], v153 offset0:18 offset1:19
	ds_read2_b32 v[182:183], v153 offset0:24 offset1:25
	ds_read2_b32 v[184:185], v153 offset0:26 offset1:27
	ds_read2_b32 v[186:187], v153 offset0:32 offset1:33
	ds_read2_b32 v[188:189], v153 offset0:34 offset1:35
	ds_read2_b32 v[190:191], v153 offset0:40 offset1:41
	ds_read2_b32 v[192:193], v153 offset0:42 offset1:43
	ds_read2_b32 v[194:195], v153 offset0:48 offset1:49
	ds_read2_b32 v[196:197], v153 offset0:50 offset1:51
	ds_read2_b32 v[198:199], v153 offset0:56 offset1:57
	ds_read2_b32 v[200:201], v153 offset0:58 offset1:59
	s_waitcnt lgkmcnt(0)
	v_fmac_f32_e32 v10, 0x3e38aa3b, v64
	v_fmac_f32_e32 v11, 0x3e38aa3b, v65
	v_fmac_f32_e32 v12, 0x3e38aa3b, v66
	v_fmac_f32_e32 v13, 0x3e38aa3b, v67
	v_fmac_f32_e32 v14, 0x3e38aa3b, v68
	v_fmac_f32_e32 v15, 0x3e38aa3b, v69
	v_fmac_f32_e32 v176, 0x3e38aa3b, v70
	v_fmac_f32_e32 v177, 0x3e38aa3b, v71
	v_fmac_f32_e32 v178, 0x3e38aa3b, v72
	v_fmac_f32_e32 v179, 0x3e38aa3b, v73
	v_fmac_f32_e32 v180, 0x3e38aa3b, v74
	v_fmac_f32_e32 v181, 0x3e38aa3b, v75
	v_fmac_f32_e32 v182, 0x3e38aa3b, v76
	v_fmac_f32_e32 v183, 0x3e38aa3b, v77
	v_fmac_f32_e32 v184, 0x3e38aa3b, v78
	v_fmac_f32_e32 v185, 0x3e38aa3b, v79
	v_fmac_f32_e32 v186, 0x3e38aa3b, v48
	v_fmac_f32_e32 v187, 0x3e38aa3b, v49
	v_fmac_f32_e32 v188, 0x3e38aa3b, v50
	v_fmac_f32_e32 v189, 0x3e38aa3b, v51
	v_fmac_f32_e32 v190, 0x3e38aa3b, v52
	v_fmac_f32_e32 v191, 0x3e38aa3b, v53
	v_fmac_f32_e32 v192, 0x3e38aa3b, v54
	v_fmac_f32_e32 v193, 0x3e38aa3b, v55
	v_fmac_f32_e32 v194, 0x3e38aa3b, v56
	v_fmac_f32_e32 v195, 0x3e38aa3b, v57
	v_fmac_f32_e32 v196, 0x3e38aa3b, v58
	v_fmac_f32_e32 v197, 0x3e38aa3b, v59
	v_fmac_f32_e32 v198, 0x3e38aa3b, v60
	v_fmac_f32_e32 v199, 0x3e38aa3b, v61
	v_fmac_f32_e32 v200, 0x3e38aa3b, v62
	v_fmac_f32_e32 v201, 0x3e38aa3b, v63
	s_and_b64 s[42:43], vcc, s[42:43]
	s_cmp_lg_u32 s32, 0
	s_cbranch_scc1 .Lna_fast
	s_mov_b64 s[100:101], s[42:43]
	s_mov_b64 s[42:43], -1
	v_mov_b32_e32 v221, 0
	v_readlane_b32 s64, v254, 24
	v_readlane_b32 s65, v254, 25
	s_and_b64 s[74:75], s[42:43], s[64:65]
	v_cndmask_b32_e64 v240, 0, 1, s[74:75]
	v_lshl_or_b32 v221, v240, 0, v221
	v_readlane_b32 s64, v254, 26
	v_readlane_b32 s65, v254, 27
	s_and_b64 s[74:75], s[42:43], s[64:65]
	v_cndmask_b32_e64 v240, 0, 1, s[74:75]
	v_lshl_or_b32 v221, v240, 1, v221
	v_readlane_b32 s64, v254, 28
	v_readlane_b32 s65, v254, 29
	s_and_b64 s[74:75], s[42:43], s[64:65]
	v_cndmask_b32_e64 v240, 0, 1, s[74:75]
	v_lshl_or_b32 v221, v240, 2, v221
	v_readlane_b32 s64, v254, 30
	v_readlane_b32 s65, v254, 31
	s_and_b64 s[74:75], s[42:43], s[64:65]
	v_cndmask_b32_e64 v240, 0, 1, s[74:75]
	v_lshl_or_b32 v221, v240, 3, v221
	v_readlane_b32 s64, v254, 32
	v_readlane_b32 s65, v254, 33
	s_and_b64 s[74:75], s[42:43], s[64:65]
	v_cndmask_b32_e64 v240, 0, 1, s[74:75]
	v_lshl_or_b32 v221, v240, 4, v221
	v_readlane_b32 s64, v254, 34
	v_readlane_b32 s65, v254, 35
	s_and_b64 s[74:75], s[42:43], s[64:65]
	v_cndmask_b32_e64 v240, 0, 1, s[74:75]
	v_lshl_or_b32 v221, v240, 5, v221
	v_readlane_b32 s64, v254, 36
	v_readlane_b32 s65, v254, 37
	s_and_b64 s[74:75], s[42:43], s[64:65]
	v_cndmask_b32_e64 v240, 0, 1, s[74:75]
	v_lshl_or_b32 v221, v240, 6, v221
	v_readlane_b32 s64, v254, 38
	v_readlane_b32 s65, v254, 39
	s_and_b64 s[74:75], s[42:43], s[64:65]
	v_cndmask_b32_e64 v240, 0, 1, s[74:75]
	v_lshl_or_b32 v221, v240, 7, v221
	v_readlane_b32 s64, v254, 40
	v_readlane_b32 s65, v254, 41
	v_readlane_b32 s74, v254, 42
	s_and_b64 s[64:65], s[42:43], s[64:65]
	v_readlane_b32 s75, v254, 43
	s_and_b64 s[74:75], s[64:65], s[74:75]
	v_cndmask_b32_e64 v240, 0, 1, s[74:75]
	v_lshl_or_b32 v221, v240, 8, v221
	v_readlane_b32 s64, v254, 44
	v_readlane_b32 s65, v254, 45
	v_readlane_b32 s74, v254, 46
	s_and_b64 s[64:65], s[42:43], s[64:65]
	v_readlane_b32 s75, v254, 47
	s_and_b64 s[74:75], s[64:65], s[74:75]
	v_cndmask_b32_e64 v240, 0, 1, s[74:75]
	v_lshl_or_b32 v221, v240, 9, v221
	v_readlane_b32 s64, v254, 48
	v_readlane_b32 s65, v254, 49
	v_readlane_b32 s74, v254, 50
	s_and_b64 s[64:65], s[42:43], s[64:65]
	v_readlane_b32 s75, v254, 51
	s_and_b64 s[74:75], s[64:65], s[74:75]
	v_cndmask_b32_e64 v240, 0, 1, s[74:75]
	v_lshl_or_b32 v221, v240, 10, v221
	v_readlane_b32 s64, v254, 52
	v_readlane_b32 s65, v254, 53
	v_readlane_b32 s74, v254, 54
	s_and_b64 s[64:65], s[42:43], s[64:65]
	v_readlane_b32 s75, v254, 55
	s_and_b64 s[74:75], s[64:65], s[74:75]
	v_cndmask_b32_e64 v240, 0, 1, s[74:75]
	v_lshl_or_b32 v221, v240, 11, v221
	v_readlane_b32 s64, v254, 56
	v_readlane_b32 s65, v254, 57
	v_readlane_b32 s74, v254, 58
	s_and_b64 s[64:65], s[42:43], s[64:65]
	v_readlane_b32 s75, v254, 59
	s_and_b64 s[74:75], s[64:65], s[74:75]
	v_cndmask_b32_e64 v240, 0, 1, s[74:75]
	v_lshl_or_b32 v221, v240, 12, v221
	v_readlane_b32 s64, v254, 60
	v_readlane_b32 s65, v254, 61
	v_readlane_b32 s74, v254, 62
	s_and_b64 s[64:65], s[42:43], s[64:65]
	v_readlane_b32 s75, v254, 63
	s_and_b64 s[74:75], s[64:65], s[74:75]
	v_cndmask_b32_e64 v240, 0, 1, s[74:75]
	v_lshl_or_b32 v221, v240, 13, v221
	v_readlane_b32 s64, v255, 0
	v_readlane_b32 s65, v255, 1
	v_readlane_b32 s74, v255, 2
	s_and_b64 s[64:65], s[42:43], s[64:65]
	v_readlane_b32 s75, v255, 3
	s_and_b64 s[74:75], s[64:65], s[74:75]
	v_cndmask_b32_e64 v240, 0, 1, s[74:75]
	v_lshl_or_b32 v221, v240, 14, v221
	v_readlane_b32 s64, v255, 4
	v_readlane_b32 s65, v255, 5
	v_readlane_b32 s74, v255, 6
	s_and_b64 s[64:65], s[42:43], s[64:65]
	v_readlane_b32 s75, v255, 7
	s_and_b64 s[74:75], s[64:65], s[74:75]
	v_cndmask_b32_e64 v240, 0, 1, s[74:75]
	v_lshl_or_b32 v221, v240, 15, v221
	v_readlane_b32 s64, v255, 8
	v_readlane_b32 s65, v255, 9
	v_readlane_b32 s74, v255, 10
	s_and_b64 s[64:65], s[42:43], s[64:65]
	v_readlane_b32 s75, v255, 11
	s_and_b64 s[74:75], s[64:65], s[74:75]
	v_cndmask_b32_e64 v240, 0, 1, s[74:75]
	v_lshl_or_b32 v221, v240, 16, v221
	v_readlane_b32 s64, v255, 12
	v_readlane_b32 s65, v255, 13
	s_and_b64 s[64:65], s[42:43], s[64:65]
	s_and_b64 s[74:75], s[64:65], s[94:95]
	v_cndmask_b32_e64 v240, 0, 1, s[74:75]
	v_lshl_or_b32 v221, v240, 17, v221
	s_and_b64 s[64:65], s[42:43], s[96:97]
	s_and_b64 s[74:75], s[64:65], s[40:41]
	v_cndmask_b32_e64 v240, 0, 1, s[74:75]
	v_lshl_or_b32 v221, v240, 18, v221
	s_and_b64 s[64:65], s[42:43], s[4:5]
	s_and_b64 s[74:75], s[64:65], s[6:7]
	v_cndmask_b32_e64 v240, 0, 1, s[74:75]
	v_lshl_or_b32 v221, v240, 19, v221
	s_and_b64 s[64:65], s[42:43], s[8:9]
	s_and_b64 s[74:75], s[64:65], s[10:11]
	v_cndmask_b32_e64 v240, 0, 1, s[74:75]
	v_lshl_or_b32 v221, v240, 20, v221
	s_and_b64 s[64:65], s[42:43], s[12:13]
	s_and_b64 s[74:75], s[64:65], s[14:15]
	v_cndmask_b32_e64 v240, 0, 1, s[74:75]
	v_lshl_or_b32 v221, v240, 21, v221
	s_and_b64 s[64:65], s[42:43], s[16:17]
	s_and_b64 s[74:75], s[64:65], s[18:19]
	v_cndmask_b32_e64 v240, 0, 1, s[74:75]
	v_lshl_or_b32 v221, v240, 22, v221
	s_and_b64 s[64:65], s[42:43], s[20:21]
	s_and_b64 s[74:75], s[64:65], s[22:23]
	v_cndmask_b32_e64 v240, 0, 1, s[74:75]
	v_lshl_or_b32 v221, v240, 23, v221
	s_and_b64 s[74:75], s[42:43], s[24:25]
	v_cndmask_b32_e64 v240, 0, 1, s[74:75]
	v_lshl_or_b32 v221, v240, 24, v221
	s_and_b64 s[74:75], s[42:43], s[26:27]
	v_cndmask_b32_e64 v240, 0, 1, s[74:75]
	v_lshl_or_b32 v221, v240, 25, v221
	s_and_b64 s[74:75], s[42:43], s[28:29]
	v_cndmask_b32_e64 v240, 0, 1, s[74:75]
	v_lshl_or_b32 v221, v240, 26, v221
	s_and_b64 s[74:75], s[42:43], s[30:31]
	v_cndmask_b32_e64 v240, 0, 1, s[74:75]
	v_lshl_or_b32 v221, v240, 27, v221
	s_and_b64 s[74:75], s[42:43], s[34:35]
	v_cndmask_b32_e64 v240, 0, 1, s[74:75]
	v_lshl_or_b32 v221, v240, 28, v221
	s_and_b64 s[74:75], s[42:43], s[36:37]
	v_cndmask_b32_e64 v240, 0, 1, s[74:75]
	v_lshl_or_b32 v221, v240, 29, v221
	s_and_b64 s[74:75], s[42:43], s[0:1]
	v_cndmask_b32_e64 v240, 0, 1, s[74:75]
	v_lshl_or_b32 v221, v240, 30, v221
	s_and_b64 s[64:65], s[42:43], s[38:39]
	v_cndmask_b32_e64 v240, 0, 1, s[64:65]
	v_lshl_or_b32 v221, v240, 31, v221
	s_mov_b64 s[42:43], s[100:101]
	s_mov_b32 s32, 1
